# attention phase only: one static s_setprio 1 for waves 4-7 (reset at the next phase)
# baseline (speedup 1.0000x reference)
; __global__ void __launch_bounds__(NTHREADS, 2) mega_fwd(Args a) {
;     ...
;     if (IN(14)) {
;         const int vcu = (G % 8 == 0) ? (int)(blockIdx.x % 8) * (G / 8) + (int)(blockIdx.x / 8) : (int)blockIdx.x;
;         for (int pu = vcu; pu < NB * NH * 4; pu += G) { const int bh = pu >> 2, j = pu & 3, b = bh >> 3, h = bh & 7;
;             attn_unit(lds, QK, VT, KM, OA, b, h, 7 - j, tid, lane, wave);
;             attn_unit(lds, QK, VT, KM, OA, b, h, j, tid, lane, wave); }
.LBB0_1507:
	v_readlane_b32 s101, v249, 18
	s_nop 3
	s_cmp_ge_u32 s101, 4
	s_cbranch_scc0 .Lattn_prio_done
	s_setprio 1

;     __host__ __device__ bool next(int i, Unit& u) const {
;         const long L = (long)i * G + c; if (L >= nwg) return false;
;         int wgid = (int)L; { const int q = nwg / NXCD, r = nwg % NXCD, xcd = wgid % NXCD, off = wgid / NXCD; wgid = (xcd < r ? xcd * (q + 1) : r * (q + 1) + (xcd - r) * q) + off; }
;         const int nig = WGM * nN, gid = wgid / nig, fm = gid * WGM, gsz = (nM - fm) < WGM ? (nM - fm) : WGM;
;         u.pm = fm + ((wgid % nig) % gsz); u.pn = (wgid % nig) / gsz; return true;
; __global__ void __launch_bounds__(NTHREADS, 2) mega_fwd(Args a) {
;     ...
;     if (IN(15)) { EpiResid E{XB, 1.f, SS + 5 * SSN}; run_gemm(lds, OA, (const bf16_t*)(ws + WS_WO), T, D, D, E); }
.LBB0_1615:
	s_setprio 0
	s_cmp_lt_i32 s30, 16
	s_cselect_b64 s[4:5], -1, 0
	s_and_b64 s[0:1], s[4:5], s[0:1]
	s_andn2_b64 vcc, exec, s[0:1]
	s_cbranch_vccnz .LBB0_1658
	s_cmpk_lt_i32 s2, 0x200
	s_cselect_b64 s[4:5], -1, 0
	s_cmpk_gt_i32 s2, 0x1ff
	v_readfirstlane_b32 s14, v197
	s_cbranch_scc1 .LBB0_1622
	s_ashr_i32 s3, s2, 31
	s_lshr_b32 s3, s3, 29
	s_add_i32 s3, s2, s3
	s_and_b32 s6, s3, -8
	s_sub_i32 s8, s2, s6
	s_cmp_gt_i32 s8, -1
	s_cbranch_scc0 .LBB0_1619
	s_lshl_b32 s9, s8, 6
	s_cbranch_execz .LBB0_1620
	s_branch .LBB0_1621
